# mixer queue: first ticket of each workgroup = its index (no contended atomic behind the grid barrier, later draws add the grid size); phase-table LDS-DMA not waited at the first draw
# baseline (speedup 1.0000x reference)
.LBB0_633:
	v_readlane_b32 s6, v254, 16
	s_lshl_b32 s92, s6, 7
	s_lshl_b64 s[6:7], s[92:93], 2
	s_waitcnt lgkmcnt(0)
	s_add_u32 s6, s48, s6
	s_addc_u32 s7, s49, s7
	s_add_u32 s6, s6, 0x4000
	s_addc_u32 s7, s7, 0
	v_writelane_b32 v254, s6, 43
	v_mov_b32_e32 v0, 0
	v_cmp_eq_u32_e32 vcc, 0, v206
	v_writelane_b32 v254, s7, 44
	s_and_saveexec_b64 s[8:9], vcc
	s_cbranch_execz .LBB0_637
	s_mov_b64 s[12:13], exec
	v_mbcnt_lo_u32_b32 v0, s12, 0
	v_mbcnt_hi_u32_b32 v0, s13, v0
	v_cmp_eq_u32_e64 s[6:7], 0, v0
	s_and_saveexec_b64 s[10:11], s[6:7]
	s_cbranch_execz .LBB0_636
	s_bcnt1_i32_b64 s6, s[12:13]
	v_mov_b32_e32 v1, s6
	v_readlane_b32 s6, v254, 43
	v_readlane_b32 s7, v254, 44
	s_nop 4
	v_mov_b32_e32 v1, s2
.LBB0_636:
	s_or_b64 exec, exec, s[10:11]
	s_nop 1
	v_readfirstlane_b32 s6, v1
	s_nop 1
	v_add_u32_e32 v0, s6, v0
.LBB0_637:
	s_or_b64 exec, exec, s[8:9]
	s_and_saveexec_b64 s[6:7], vcc
	s_cbranch_execz .LBB0_639
	v_readlane_b32 s8, v254, 10
	s_nop 1
	v_mov_b32_e32 v1, s8
	ds_write_b32 v1, v0
.LBB0_639:
	s_or_b64 exec, exec, s[6:7]
	v_readlane_b32 s6, v254, 10
	s_waitcnt lgkmcnt(0)
	s_barrier
	v_mov_b32_e32 v0, s6
	v_readlane_b32 s6, v254, 16
	ds_read_b32 v0, v0
	s_cmp_lg_u32 s6, 3
	s_cselect_b64 s[8:9], -1, 0
	s_and_b64 s[6:7], s[8:9], exec
	s_movk_i32 s6, 0x7d0
	s_cselect_b32 s56, s6, 0x780
	s_waitcnt lgkmcnt(0)
	v_cmp_le_i32_e32 vcc, s56, v0
	v_readfirstlane_b32 s12, v0
	s_cbranch_vccnz .LBB0_815
	v_writelane_b32 v254, s8, 48
	s_ashr_i32 s6, s0, 8
	s_lshl_b32 s10, s5, 5
	v_writelane_b32 v254, s9, 49
	s_bfe_u32 s8, s0, 0x20006
	s_lshl_b32 s7, s8, 4
	v_writelane_b32 v254, s7, 42
	s_mul_i32 s7, s6, 0x5000
	s_add_i32 s72, s7, 0
	s_lshl_b32 s7, s5, 12
	v_writelane_b32 v254, s8, 34
	s_add_i32 s9, s7, 0
	s_lshl_b32 s7, s6, 12
	s_lshl_b32 s8, s8, 10
	v_writelane_b32 v254, s10, 50
	s_or_b32 s10, s10, 16
	s_or_b32 s8, s8, s7
	s_lshl_b32 s7, s5, 4
	v_writelane_b32 v254, s10, 51
	v_writelane_b32 v254, s7, 52
	s_andn2_b32 s7, s7, 63
	v_writelane_b32 v254, s7, 53
	s_mul_i32 s7, s5, 0x1400
	s_andn2_b32 s0, s0, 63
	v_writelane_b32 v254, s9, 40
	s_add_i32 s7, s9, s7
	s_add_i32 s65, s0, 0
	s_lshl_b32 s0, s5, 7
	v_writelane_b32 v254, s7, 45
	s_lshl_b32 s7, s6, 6
	s_cmp_eq_u32 s6, 1
	s_cselect_b64 s[46:47], -1, 0
	s_cmp_lt_u32 s5, 4
	v_writelane_b32 v254, s7, 38
	s_cselect_b64 s[88:89], -1, 0
	s_add_i32 s5, s8, 0x3fc000
	v_writelane_b32 v254, s8, 54
	s_add_u32 s6, s48, 0x7c00180
	v_writelane_b32 v254, s5, 55
	s_addc_u32 s7, s49, 0
	v_writelane_b32 v254, s6, 56
	s_mov_b32 s80, 4
	s_mov_b32 s18, 1
	v_writelane_b32 v254, s7, 57
	s_nop 0
	v_readlane_b32 s8, v254, 19
	s_add_u32 s8, s48, 0x1b700000
	v_readlane_b32 s9, v254, 20
	v_readlane_b32 s11, v254, 22
	s_addc_u32 s5, s49, 0
	v_readlane_b32 s10, v254, 21
	v_writelane_b32 v254, s5, 58
	s_and_b32 s9, s5, 0xffff
	s_mov_b32 s11, s51
	v_writelane_b32 v254, s8, 19
	s_add_u32 s70, s48, 0x7c00000
	s_addc_u32 s71, s49, 0
	v_writelane_b32 v254, s9, 20
	v_writelane_b32 v254, s10, 21
	v_writelane_b32 v254, s11, 22
	s_add_u32 s5, s48, 0x5000
	v_writelane_b32 v254, s5, 59
	s_addc_u32 s5, s49, 0
	s_add_u32 s6, s48, 0x1d800000
	v_writelane_b32 v254, s5, 60
	s_addc_u32 s7, s49, 0
	v_writelane_b32 v254, s6, 61
	s_add_u32 s5, s48, 0x6400
	s_nop 0
	v_writelane_b32 v254, s7, 62
	v_writelane_b32 v254, s5, 63
	s_addc_u32 s5, s49, 0
	v_writelane_b32 v255, s5, 0
	s_add_u32 s5, s48, 0x6000
	v_writelane_b32 v255, s5, 1
	s_addc_u32 s5, s49, 0
	v_readlane_b32 s8, v254, 23
	s_add_u32 s8, s48, 0x1c800000
	v_writelane_b32 v255, s5, 2
	v_readlane_b32 s9, v254, 24
	v_readlane_b32 s11, v254, 26
	s_addc_u32 s5, s49, 0
	v_readlane_b32 s10, v254, 25
	s_and_b32 s9, s5, 0xffff
	s_mov_b32 s11, s51
	v_writelane_b32 v254, s8, 23
	v_writelane_b32 v255, s5, 3
	s_add_u32 s5, s48, 0x18c00000
	v_writelane_b32 v254, s9, 24
	v_writelane_b32 v254, s10, 25
	v_writelane_b32 v254, s11, 26
	v_writelane_b32 v254, s5, 46
	s_addc_u32 s5, s49, 0
	s_add_i32 s0, s0, 0
	v_writelane_b32 v254, s5, 47
	v_writelane_b32 v255, s0, 4
	s_branch .LBB0_642

.LBB0_805:
	v_mov_b32_e32 v0, 0
	v_cmp_ne_u32_e32 vcc, 0, v206
	v_cmp_eq_u32_e64 s[6:7], 0, v206
	s_and_saveexec_b64 s[10:11], s[6:7]
	s_cbranch_execz .LBB0_809
	s_mov_b64 s[16:17], exec
	v_mbcnt_lo_u32_b32 v0, s16, 0
	v_mbcnt_hi_u32_b32 v0, s17, v0
	v_cmp_eq_u32_e64 s[8:9], 0, v0
	s_and_saveexec_b64 s[12:13], s[8:9]
	s_cbranch_execz .LBB0_808
	s_bcnt1_i32_b64 s0, s[16:17]
	v_readlane_b32 s8, v254, 43
	v_mov_b32_e32 v1, s0
	v_readlane_b32 s9, v254, 44
	s_nop 4
	v_readlane_b32 s100, v253, 0
	v_readlane_b32 s101, v253, 1
	s_nop 4
	s_load_dword s100, s[100:101], 0xb0
	global_atomic_add v1, v33, v1, s[8:9] sc0
.LBB0_808:
	s_or_b64 exec, exec, s[12:13]
	s_waitcnt vmcnt(0) lgkmcnt(0)
	v_readfirstlane_b32 s0, v1
	s_add_i32 s0, s0, s100
	v_add_u32_e32 v0, s0, v0
